# attention loop: ALiBi bias as one fmamk per score with the per-lane term folded into max/exp, 17-op row max, sqrt of key-norm prefix max hoisted to item prologue, K fragment reads issued before the dr
# speedup vs baseline: 1.0456x; 1.0137x over previous
.LBB0_1360:
	s_or_b64 exec, exec, s[12:13]
	s_and_b64 vcc, exec, s[6:7]
	s_cbranch_vccnz .LBB0_1362
	v_max_f32_e32 v2, v2, v2
	v_max_f32_e32 v4, v3, v3
	v_max_f32_e32 v2, v4, v2
	ds_bpermute_b32 v3, v207, v2
	v_cmp_gt_u32_e32 vcc, 2, v191
	s_lshl_b32 s6, s70, 9
	s_add_i32 s6, s6, 0
	s_waitcnt lgkmcnt(0)
	v_max_f32_e32 v3, v3, v3
	v_max_f32_e32 v3, v2, v3
	v_cndmask_b32_e64 v2, v3, v2, s[0:1]
	ds_bpermute_b32 v3, v208, v2
	s_waitcnt lgkmcnt(0)
	v_max_f32_e32 v3, v3, v3
	v_max_f32_e32 v3, v2, v3
	v_cndmask_b32_e32 v2, v3, v2, vcc
	ds_bpermute_b32 v3, v209, v2
	v_cmp_gt_u32_e32 vcc, 4, v191
	s_waitcnt lgkmcnt(0)
	v_max_f32_e32 v3, v3, v3
	v_max_f32_e32 v3, v2, v3
	v_cndmask_b32_e32 v2, v3, v2, vcc
	ds_bpermute_b32 v3, v210, v2
	v_cmp_gt_u32_e32 vcc, 8, v191
	s_waitcnt lgkmcnt(0)
	v_max_f32_e32 v3, v3, v3
	v_max_f32_e32 v3, v2, v3
	v_cndmask_b32_e32 v2, v3, v2, vcc
	ds_bpermute_b32 v3, v211, v2
	v_cmp_gt_u32_e32 vcc, 16, v191
	s_waitcnt lgkmcnt(0)
	v_max_f32_e32 v3, v3, v3
	v_max_f32_e32 v3, v2, v3
	v_cndmask_b32_e32 v2, v3, v2, vcc
	ds_bpermute_b32 v3, v212, v2
	v_max_f32_e32 v5, v2, v2
	v_cmp_gt_u32_e32 vcc, 32, v191
	s_waitcnt lgkmcnt(0)
	v_max_f32_e32 v3, v3, v3
	v_max_f32_e32 v3, v5, v3
	v_cndmask_b32_e32 v3, v3, v2, vcc
	ds_bpermute_b32 v2, v207, v3
	v_lshl_add_u32 v5, v191, 3, s6
	s_waitcnt lgkmcnt(0)
	v_cndmask_b32_e64 v2, v2, 0, s[0:1]
	v_max_f32_e32 v2, v2, v2
	v_max_f32_e32 v2, v4, v2
	v_mul_f32_e32 v7, 0x4f800000, v2
	v_cmp_gt_f32_e32 vcc, s38, v2
	s_nop 1
	v_cndmask_b32_e32 v6, v2, v7, vcc
	v_sqrt_f32_e32 v7, v6
	s_nop 0
	v_add_u32_e32 v8, -1, v7
	v_add_u32_e32 v9, 1, v7
	v_fma_f32 v10, -v8, v7, v6
	v_fma_f32 v11, -v9, v7, v6
	v_cmp_ge_f32_e64 s[12:13], 0, v10
	s_nop 1
	v_cndmask_b32_e64 v7, v7, v8, s[12:13]
	v_cmp_lt_f32_e64 s[12:13], 0, v11
	s_nop 1
	v_cndmask_b32_e64 v7, v7, v9, s[12:13]
	v_mul_f32_e32 v8, 0x37800000, v7
	v_cndmask_b32_e32 v7, v7, v8, vcc
	v_cmp_class_f32_e32 vcc, v6, v213
	s_nop 1
	v_cndmask_b32_e32 v2, v7, v6, vcc
	v_mul_f32_e32 v7, 0x4f800000, v3
	v_cmp_gt_f32_e32 vcc, s38, v3
	s_nop 1
	v_cndmask_b32_e32 v6, v3, v7, vcc
	v_sqrt_f32_e32 v7, v6
	s_nop 0
	v_add_u32_e32 v8, -1, v7
	v_add_u32_e32 v9, 1, v7
	v_fma_f32 v10, -v8, v7, v6
	v_fma_f32 v11, -v9, v7, v6
	v_cmp_ge_f32_e64 s[12:13], 0, v10
	s_nop 1
	v_cndmask_b32_e64 v7, v7, v8, s[12:13]
	v_cmp_lt_f32_e64 s[12:13], 0, v11
	s_nop 1
	v_cndmask_b32_e64 v7, v7, v9, s[12:13]
	v_mul_f32_e32 v8, 0x37800000, v7
	v_cndmask_b32_e32 v7, v7, v8, vcc
	v_cmp_class_f32_e32 vcc, v6, v213
	s_nop 1
	v_cndmask_b32_e32 v3, v7, v6, vcc
	v_add_u32_e32 v4, 0x11800, v5
	ds_write_b64 v4, v[2:3]

.LBB0_1380:
	v_mov_b32_e32 v248, s13
	ds_read2_b32 v[248:249], v248 offset0:1 offset1:129
	ds_read_b128 v[66:69], v222
	ds_read_b128 v[146:149], v222 offset:32
	ds_read_b128 v[70:73], v222 offset:8704
	ds_read_b128 v[150:153], v222 offset:8736
	ds_read_b128 v[154:157], v222 offset:64
	ds_read_b128 v[158:161], v222 offset:96
	ds_read_b128 v[162:165], v222 offset:8768
	ds_read_b128 v[228:231], v222 offset:8800
	s_add_i32 s46, s35, -1
	s_cmp_ge_i32 s46, s26
	s_cbranch_scc1 .LBB0_1384
	s_add_i32 s0, s12, s27
	s_addk_i32 s0, 0x140
	v_cvt_f32_i32_e32 v251, s0
	s_waitcnt lgkmcnt(8)
	v_mov_b32_e32 v252, v248
	v_mov_b32_e32 v250, v249
	v_pk_mul_f32 v[248:249], v[200:201], v[250:251]
	s_nop 0
	v_fma_f32 v250, v178, v252, -v249
	v_sub_f32_e32 v248, v248, v249
	v_cmp_lt_f32_e32 vcc, v250, v180
	v_cmp_lt_f32_e64 s[0:1], v248, v181
	s_and_b64 s[0:1], vcc, s[0:1]
	s_and_b64 vcc, exec, s[0:1]
	s_mov_b32 s0, s46
	s_cbranch_vccnz .LBB0_1383
	s_add_i32 s0, s6, 1
	s_ashr_i32 s1, s0, 31
	s_lshl_b64 s[0:1], s[0:1], 14
	v_lshl_add_u64 v[250:251], v[196:197], 0, s[0:1]
	v_add_co_u32_e32 v252, vcc, 0x2000, v250
	v_lshl_add_u64 v[248:249], v[198:199], 0, s[0:1]
	s_nop 0
	v_addc_co_u32_e32 v253, vcc, 0, v251, vcc
	global_load_dwordx4 v[98:101], v[250:251], off
	global_load_dwordx4 v[102:105], v[252:253], off
	global_load_dwordx4 v[106:109], v[248:249], off
	v_add_co_u32_e32 v248, vcc, 0x2000, v248
	s_mov_b32 s0, s26
	s_nop 0
	v_addc_co_u32_e32 v249, vcc, 0, v249, vcc
	global_load_dwordx4 v[110:113], v[248:249], off

.LBB0_1384:
	s_add_i32 s0, s34, -2
	s_cmp_lt_i32 s0, 1
	s_cbranch_scc1 .LBB0_1388
	s_waitcnt lgkmcnt(7)
	v_mfma_f32_32x32x16_bf16 v[82:97], v[66:69], v[130:133], 0
	s_waitcnt lgkmcnt(5)
	v_mfma_f32_32x32x16_bf16 v[66:81], v[70:73], v[130:133], 0
	v_mfma_f32_32x32x16_bf16 v[82:97], v[146:149], v[134:137], v[82:97]
	s_waitcnt lgkmcnt(4)
	v_mfma_f32_32x32x16_bf16 v[66:81], v[150:153], v[134:137], v[66:81]
	s_waitcnt lgkmcnt(3)
	v_mfma_f32_32x32x16_bf16 v[82:97], v[154:157], v[138:141], v[82:97]
	s_waitcnt lgkmcnt(1)
	v_mfma_f32_32x32x16_bf16 v[66:81], v[162:165], v[138:141], v[66:81]
	v_mfma_f32_32x32x16_bf16 v[82:97], v[158:161], v[142:145], v[82:97]
	ds_read_b128 v[162:165], v221 offset:17408
	ds_read_b128 v[146:149], v221 offset:17440
	ds_read_b128 v[166:169], v221 offset:22016
	ds_read_b128 v[150:153], v221 offset:22048
	ds_read_b128 v[170:173], v221 offset:26624
	ds_read_b128 v[154:157], v221 offset:26656
	ds_read_b128 v[174:177], v221 offset:31232
	ds_read_b128 v[158:161], v221 offset:31264
	s_waitcnt lgkmcnt(8)
	v_mfma_f32_32x32x16_bf16 v[66:81], v[228:231], v[142:145], v[66:81]
	v_add_u32_e32 v184, s12, v223
	v_add_u32_e32 v184, 0xc0, v184
	v_cvt_f32_i32_e32 v236, v184
	v_mul_f32_e64 v245, -v201, v236
	v_mov_b32_e32 v188, v82
	v_fmamk_f32 v234, v201, 0x3f800000, v83
	v_fmamk_f32 v229, v201, 0x40000000, v84
	v_fmamk_f32 v231, v201, 0x40400000, v85
	v_fmamk_f32 v184, v201, 0x41000000, v86
	v_fmamk_f32 v227, v201, 0x41100000, v87
	v_fmamk_f32 v86, v201, 0x41200000, v88
	v_fmamk_f32 v88, v201, 0x41300000, v89
	v_fmamk_f32 v233, v201, 0x42000000, v66
	v_fmamk_f32 v235, v201, 0x42040000, v67
	v_fmamk_f32 v230, v201, 0x42080000, v68
	v_fmamk_f32 v232, v201, 0x420c0000, v69
	v_fmamk_f32 v185, v201, 0x42200000, v70
	v_fmamk_f32 v228, v201, 0x42240000, v71
	v_fmamk_f32 v87, v201, 0x42280000, v72
	v_fmamk_f32 v89, v201, 0x422c0000, v73
	v_fmamk_f32 v82, v201, 0x41800000, v90
	v_fmamk_f32 v84, v201, 0x41880000, v91
	v_fmamk_f32 v83, v201, 0x42400000, v74
	v_fmamk_f32 v85, v201, 0x42440000, v75
	v_fmamk_f32 v74, v201, 0x41900000, v92
	v_fmamk_f32 v75, v201, 0x42480000, v76
	v_fmamk_f32 v76, v201, 0x41980000, v93
	v_fmamk_f32 v77, v201, 0x424c0000, v77
	v_fmamk_f32 v70, v201, 0x41c00000, v94
	v_fmamk_f32 v72, v201, 0x41c80000, v95
	v_fmamk_f32 v71, v201, 0x42600000, v78
	v_fmamk_f32 v73, v201, 0x42640000, v79
	v_fmamk_f32 v67, v201, 0x42680000, v80
	v_fmamk_f32 v69, v201, 0x426c0000, v81
	v_fmamk_f32 v66, v201, 0x41d00000, v96
	v_fmamk_f32 v68, v201, 0x41d80000, v97
	v_max3_f32 v78, v188, v234, v233
	v_max3_f32 v247, v82, v84, v83
	v_max3_f32 v78, v78, v235, v229
	v_max3_f32 v247, v247, v85, v74
	v_max3_f32 v78, v78, v230, v231
	v_max3_f32 v247, v247, v75, v76
	v_max3_f32 v78, v78, v232, v184
	v_max3_f32 v247, v247, v77, v70
	v_max3_f32 v78, v78, v227, v185
	v_max3_f32 v247, v247, v72, v71
	v_max3_f32 v78, v78, v228, v86
	v_max3_f32 v247, v247, v73, v67
	v_max3_f32 v78, v78, v88, v87
	v_max3_f32 v247, v247, v69, v66
	v_max_f32_e32 v78, v78, v89
	v_max_f32_e32 v247, v247, v68
	v_max_f32_e32 v78, v78, v247
	v_add_f32_e32 v78, v245, v78
	ds_bpermute_b32 v79, v1, v78
	s_waitcnt lgkmcnt(0)
	v_max_f32_e32 v79, v79, v79
	v_max_f32_e32 v78, v78, v79
	v_cmp_gt_f32_e32 vcc, v78, v226
	s_cbranch_vccz .LBB0_1387
	v_max_f32_e32 v78, v78, v78
	v_max_f32_e32 v79, v226, v226
	v_max_f32_e32 v79, v79, v78
	v_sub_f32_e32 v78, v226, v79
	v_exp_f32_e32 v78, v78
	v_mov_b32_e32 v226, v79
	v_mul_f32_e32 v224, v224, v78
	v_pk_mul_f32 v[64:65], v[64:65], v[78:79] op_sel_hi:[1,0]
	v_pk_mul_f32 v[62:63], v[62:63], v[78:79] op_sel_hi:[1,0]
	v_pk_mul_f32 v[60:61], v[60:61], v[78:79] op_sel_hi:[1,0]
	v_pk_mul_f32 v[58:59], v[58:59], v[78:79] op_sel_hi:[1,0]
	v_pk_mul_f32 v[56:57], v[56:57], v[78:79] op_sel_hi:[1,0]
	v_pk_mul_f32 v[54:55], v[54:55], v[78:79] op_sel_hi:[1,0]
	v_pk_mul_f32 v[52:53], v[52:53], v[78:79] op_sel_hi:[1,0]
	v_pk_mul_f32 v[50:51], v[50:51], v[78:79] op_sel_hi:[1,0]
	v_pk_mul_f32 v[48:49], v[48:49], v[78:79] op_sel_hi:[1,0]
	v_pk_mul_f32 v[46:47], v[46:47], v[78:79] op_sel_hi:[1,0]
	v_pk_mul_f32 v[44:45], v[44:45], v[78:79] op_sel_hi:[1,0]
	v_pk_mul_f32 v[42:43], v[42:43], v[78:79] op_sel_hi:[1,0]
	v_pk_mul_f32 v[40:41], v[40:41], v[78:79] op_sel_hi:[1,0]
	v_pk_mul_f32 v[38:39], v[38:39], v[78:79] op_sel_hi:[1,0]
	v_pk_mul_f32 v[36:37], v[36:37], v[78:79] op_sel_hi:[1,0]
	v_pk_mul_f32 v[34:35], v[34:35], v[78:79] op_sel_hi:[1,0]
	v_pk_mul_f32 v[32:33], v[32:33], v[78:79] op_sel_hi:[1,0]
	v_pk_mul_f32 v[30:31], v[30:31], v[78:79] op_sel_hi:[1,0]
	v_pk_mul_f32 v[28:29], v[28:29], v[78:79] op_sel_hi:[1,0]
	v_pk_mul_f32 v[26:27], v[26:27], v[78:79] op_sel_hi:[1,0]
	v_pk_mul_f32 v[24:25], v[24:25], v[78:79] op_sel_hi:[1,0]
	v_pk_mul_f32 v[22:23], v[22:23], v[78:79] op_sel_hi:[1,0]
	v_pk_mul_f32 v[20:21], v[20:21], v[78:79] op_sel_hi:[1,0]
	v_pk_mul_f32 v[18:19], v[18:19], v[78:79] op_sel_hi:[1,0]
	v_pk_mul_f32 v[16:17], v[16:17], v[78:79] op_sel_hi:[1,0]
	v_pk_mul_f32 v[14:15], v[14:15], v[78:79] op_sel_hi:[1,0]
	v_pk_mul_f32 v[12:13], v[12:13], v[78:79] op_sel_hi:[1,0]
	v_pk_mul_f32 v[10:11], v[10:11], v[78:79] op_sel_hi:[1,0]
	v_pk_mul_f32 v[8:9], v[8:9], v[78:79] op_sel_hi:[1,0]
	v_pk_mul_f32 v[6:7], v[6:7], v[78:79] op_sel_hi:[1,0]
	v_pk_mul_f32 v[4:5], v[4:5], v[78:79] op_sel_hi:[1,0]
	v_pk_mul_f32 v[2:3], v[2:3], v[78:79] op_sel_hi:[1,0]
.LBB0_1387:
	v_sub_f32_e32 v246, v226, v245
	v_sub_f32_e32 v78, v188, v246
	v_exp_f32_e32 v236, v78
	v_sub_f32_e32 v78, v233, v246
	v_exp_f32_e32 v237, v78
	v_sub_f32_e32 v78, v234, v246
	v_sub_f32_e32 v79, v235, v246
	v_exp_f32_e32 v78, v78
	v_exp_f32_e32 v188, v79
	v_add_f32_e32 v79, v236, v237
	v_sub_f32_e32 v86, v86, v246
	v_sub_f32_e32 v82, v82, v246
	v_pk_add_f32 v[80:81], v[78:79], v[188:189]
	v_sub_f32_e32 v79, v229, v246
	v_pk_add_f32 v[80:81], v[80:81], v[80:81] op_sel_hi:[0,1]
	v_sub_f32_e32 v80, v230, v246
	v_exp_f32_e32 v234, v80
	v_sub_f32_e32 v80, v231, v246
	v_exp_f32_e32 v79, v79
	v_exp_f32_e32 v90, v80
	v_sub_f32_e32 v80, v232, v246
	v_exp_f32_e32 v80, v80
	v_add_f32_e32 v91, v79, v234
	v_sub_f32_e32 v74, v74, v246
	v_sub_f32_e32 v70, v70, v246
	v_pk_add_f32 v[92:93], v[90:91], v[80:81]
	v_sub_f32_e32 v81, v184, v246
	v_pk_add_f32 v[92:93], v[92:93], v[92:93] op_sel_hi:[0,1]
	v_sub_f32_e32 v91, v185, v246
	v_sub_f32_e32 v92, v227, v246
	v_exp_f32_e32 v81, v81
	v_exp_f32_e32 v91, v91
	v_exp_f32_e32 v94, v92
	v_sub_f32_e32 v92, v228, v246
	v_exp_f32_e32 v92, v92
	v_add_f32_e32 v95, v81, v91
	v_sub_f32_e32 v66, v66, v246
	v_pk_add_f32 v[96:97], v[94:95], v[92:93]
	v_exp_f32_e32 v93, v86
	v_sub_f32_e32 v86, v87, v246
	v_pk_add_f32 v[96:97], v[96:97], v[96:97] op_sel_hi:[0,1]
	v_exp_f32_e32 v95, v86
	v_sub_f32_e32 v86, v88, v246
	v_sub_f32_e32 v87, v89, v246
	v_exp_f32_e32 v86, v86
	v_exp_f32_e32 v96, v87
	v_add_f32_e32 v87, v93, v95
	v_pk_add_f32 v[88:89], v[86:87], v[96:97]
	v_exp_f32_e32 v87, v82
	v_sub_f32_e32 v82, v83, v246
	v_pk_add_f32 v[88:89], v[88:89], v[88:89] op_sel_hi:[0,1]
	v_exp_f32_e32 v97, v82
	v_sub_f32_e32 v82, v84, v246
	v_sub_f32_e32 v83, v85, v246
	v_exp_f32_e32 v82, v82
	v_exp_f32_e32 v88, v83
	v_add_f32_e32 v83, v87, v97
	v_pk_add_f32 v[84:85], v[82:83], v[88:89]
	v_exp_f32_e32 v83, v74
	v_sub_f32_e32 v74, v75, v246
	v_exp_f32_e32 v89, v74
	v_sub_f32_e32 v74, v76, v246
	v_pk_add_f32 v[84:85], v[84:85], v[84:85] op_sel_hi:[0,1]
	v_exp_f32_e32 v76, v74
	v_sub_f32_e32 v74, v77, v246
	v_exp_f32_e32 v84, v74
	v_add_f32_e32 v77, v83, v89
	v_pk_add_f32 v[74:75], v[76:77], v[84:85]
	v_exp_f32_e32 v77, v70
	v_sub_f32_e32 v70, v71, v246
	v_exp_f32_e32 v85, v70
	v_sub_f32_e32 v70, v72, v246
	v_pk_add_f32 v[184:185], v[74:75], v[74:75] op_sel_hi:[0,1]
	v_exp_f32_e32 v228, v70
	v_sub_f32_e32 v70, v73, v246
	v_exp_f32_e32 v184, v70
	v_add_f32_e32 v229, v77, v85
	v_cvt_pk_bf16_f32 v72, v91, v92
	v_cvt_pk_bf16_f32 v73, v95, v96
	v_pk_add_f32 v[70:71], v[228:229], v[184:185]
	v_exp_f32_e32 v185, v66
	v_sub_f32_e32 v66, v67, v246
	v_exp_f32_e32 v227, v66
	v_sub_f32_e32 v66, v68, v246
	v_pk_add_f32 v[230:231], v[70:71], v[70:71] op_sel_hi:[0,1]
	v_exp_f32_e32 v232, v66
	v_sub_f32_e32 v66, v69, v246
	v_exp_f32_e32 v230, v66
	v_add_f32_e32 v233, v185, v227
	v_cvt_pk_bf16_f32 v68, v81, v94
	v_cvt_pk_bf16_f32 v69, v93, v86
	v_pk_add_f32 v[66:67], v[232:233], v[230:231]
	v_cvt_pk_bf16_f32 v70, v237, v188
	v_add_f32_e32 v66, v66, v67
	v_add_f32_e32 v224, v224, v66
	v_cvt_pk_bf16_f32 v66, v236, v78
	v_cvt_pk_bf16_f32 v67, v79, v90
	v_cvt_pk_bf16_f32 v71, v234, v80
	v_cvt_pk_bf16_f32 v74, v87, v82
	v_cvt_pk_bf16_f32 v75, v83, v76
	v_cvt_pk_bf16_f32 v76, v77, v228
	v_cvt_pk_bf16_f32 v77, v185, v232
	v_cvt_pk_bf16_f32 v78, v97, v88
	v_cvt_pk_bf16_f32 v79, v89, v84
	v_cvt_pk_bf16_f32 v80, v85, v184
	v_cvt_pk_bf16_f32 v81, v227, v230
	ds_read_b128 v[82:85], v221 offset:17472
	ds_read_b128 v[86:89], v221 offset:17504
	ds_read_b128 v[90:93], v221 offset:22080
	ds_read_b128 v[94:97], v221 offset:22112
	ds_read_b128 v[228:231], v221 offset:26688
	ds_read_b128 v[232:235], v221 offset:26720
	ds_read_b128 v[236:239], v221 offset:31296
	ds_read_b128 v[240:243], v221 offset:31328
	v_mfma_f32_32x32x16_bf16 v[50:65], v[162:165], v[66:69], v[50:65]
	v_mfma_f32_32x32x16_bf16 v[34:49], v[166:169], v[66:69], v[34:49]
	v_mfma_f32_32x32x16_bf16 v[18:33], v[170:173], v[66:69], v[18:33]
	v_mfma_f32_32x32x16_bf16 v[2:17], v[174:177], v[66:69], v[2:17]
	v_mfma_f32_32x32x16_bf16 v[50:65], v[146:149], v[74:77], v[50:65]
	v_mfma_f32_32x32x16_bf16 v[34:49], v[150:153], v[74:77], v[34:49]
	v_mfma_f32_32x32x16_bf16 v[18:33], v[154:157], v[74:77], v[18:33]
	v_mfma_f32_32x32x16_bf16 v[2:17], v[158:161], v[74:77], v[2:17]
	s_waitcnt lgkmcnt(7)
	v_mfma_f32_32x32x16_bf16 v[50:65], v[82:85], v[70:73], v[50:65]
	s_waitcnt lgkmcnt(5)
	v_mfma_f32_32x32x16_bf16 v[34:49], v[90:93], v[70:73], v[34:49]
	s_waitcnt lgkmcnt(3)
	v_mfma_f32_32x32x16_bf16 v[18:33], v[228:231], v[70:73], v[18:33]
	s_waitcnt lgkmcnt(1)
	v_mfma_f32_32x32x16_bf16 v[2:17], v[236:239], v[70:73], v[2:17]
	v_mfma_f32_32x32x16_bf16 v[50:65], v[86:89], v[78:81], v[50:65]
	v_mfma_f32_32x32x16_bf16 v[34:49], v[94:97], v[78:81], v[34:49]
	v_mfma_f32_32x32x16_bf16 v[18:33], v[232:235], v[78:81], v[18:33]
	s_waitcnt lgkmcnt(0)
	v_mfma_f32_32x32x16_bf16 v[2:17], v[240:243], v[78:81], v[2:17]

.LBB0_1390:
	s_andn2_b64 vcc, exec, s[0:1]
	s_waitcnt lgkmcnt(0)
	s_barrier
	s_cbranch_vccnz .LBB0_1396
	v_mov_b32_e32 v248, s13
	ds_read2st64_b32 v[248:249], v248 offset1:2
	ds_read_b128 v[66:69], v222 offset:35840
	ds_read_b128 v[146:149], v222 offset:35872
	ds_read_b128 v[70:73], v222 offset:44544
	ds_read_b128 v[150:153], v222 offset:44576
	ds_read_b128 v[154:157], v222 offset:35904
	ds_read_b128 v[158:161], v222 offset:35936
	ds_read_b128 v[162:165], v222 offset:44608
	ds_read_b128 v[228:231], v222 offset:44640
	s_cmp_ge_i32 s35, s26
	s_cbranch_scc1 .LBB0_1397
	s_add_i32 s0, s12, s27
	s_addk_i32 s0, 0x180
	v_cvt_f32_i32_e32 v250, s0
	s_waitcnt lgkmcnt(8)
	v_mul_f32_e32 v252, v201, v250
	v_mov_b32_e32 v250, v248
	v_mov_b32_e32 v251, v249
	v_mov_b32_e32 v248, v252
	v_pk_fma_f32 v[248:249], v[178:179], v[250:251], v[248:249] op_sel_hi:[1,1,0] neg_lo:[0,0,1] neg_hi:[0,0,1]
	s_nop 0
	v_cmp_lt_f32_e32 vcc, v249, v181
	v_cmp_lt_f32_e64 s[0:1], v248, v180
	s_and_b64 s[0:1], s[0:1], vcc
	s_and_b64 vcc, exec, s[0:1]
	s_mov_b32 s0, s35
	s_cbranch_vccnz .LBB0_1394
	s_ashr_i32 s7, s6, 31
	s_lshl_b64 s[0:1], s[6:7], 14
	v_lshl_add_u64 v[250:251], v[196:197], 0, s[0:1]
	v_add_co_u32_e32 v252, vcc, 0x2000, v250
	v_lshl_add_u64 v[248:249], v[198:199], 0, s[0:1]
	s_nop 0
	v_addc_co_u32_e32 v253, vcc, 0, v251, vcc
	global_load_dwordx4 v[114:117], v[250:251], off
	global_load_dwordx4 v[118:121], v[252:253], off
	global_load_dwordx4 v[122:125], v[248:249], off
	v_add_co_u32_e32 v248, vcc, 0x2000, v248
	s_mov_b32 s0, s26
	s_nop 0
	v_addc_co_u32_e32 v249, vcc, 0, v249, vcc
	global_load_dwordx4 v[126:129], v[248:249], off

.LBB0_1398:
	s_waitcnt lgkmcnt(7)
	v_mfma_f32_32x32x16_bf16 v[82:97], v[66:69], v[130:133], 0
	s_waitcnt lgkmcnt(5)
	v_mfma_f32_32x32x16_bf16 v[66:81], v[70:73], v[130:133], 0
	v_mfma_f32_32x32x16_bf16 v[82:97], v[146:149], v[134:137], v[82:97]
	s_waitcnt lgkmcnt(4)
	v_mfma_f32_32x32x16_bf16 v[66:81], v[150:153], v[134:137], v[66:81]
	s_waitcnt lgkmcnt(3)
	v_mfma_f32_32x32x16_bf16 v[82:97], v[154:157], v[138:141], v[82:97]
	s_waitcnt lgkmcnt(1)
	v_mfma_f32_32x32x16_bf16 v[66:81], v[162:165], v[138:141], v[66:81]
	v_mfma_f32_32x32x16_bf16 v[82:97], v[158:161], v[142:145], v[82:97]
	ds_read_b128 v[166:169], v221 offset:53248
	ds_read_b128 v[150:153], v221 offset:53280
	ds_read_b128 v[162:165], v225 offset:13824
	ds_read_b128 v[146:149], v225 offset:13856
	ds_read_b128 v[170:173], v221 offset:57856
	ds_read_b128 v[154:157], v221 offset:57888
	ds_read_b128 v[174:177], v221 offset:62464
	ds_read_b128 v[158:161], v221 offset:62496
	s_waitcnt lgkmcnt(8)
	v_mfma_f32_32x32x16_bf16 v[66:81], v[228:231], v[142:145], v[66:81]
	v_add_u32_e32 v184, s12, v223
	v_add_u32_e32 v184, 0x100, v184
	v_cvt_f32_i32_e32 v236, v184
	v_mul_f32_e64 v245, -v201, v236
	v_mov_b32_e32 v188, v82
	v_fmamk_f32 v234, v201, 0x3f800000, v83
	v_fmamk_f32 v229, v201, 0x40000000, v84
	v_fmamk_f32 v231, v201, 0x40400000, v85
	v_fmamk_f32 v184, v201, 0x41000000, v86
	v_fmamk_f32 v227, v201, 0x41100000, v87
	v_fmamk_f32 v86, v201, 0x41200000, v88
	v_fmamk_f32 v88, v201, 0x41300000, v89
	v_fmamk_f32 v233, v201, 0x42000000, v66
	v_fmamk_f32 v235, v201, 0x42040000, v67
	v_fmamk_f32 v230, v201, 0x42080000, v68
	v_fmamk_f32 v232, v201, 0x420c0000, v69
	v_fmamk_f32 v185, v201, 0x42200000, v70
	v_fmamk_f32 v228, v201, 0x42240000, v71
	v_fmamk_f32 v87, v201, 0x42280000, v72
	v_fmamk_f32 v89, v201, 0x422c0000, v73
	v_fmamk_f32 v82, v201, 0x41800000, v90
	v_fmamk_f32 v84, v201, 0x41880000, v91
	v_fmamk_f32 v83, v201, 0x42400000, v74
	v_fmamk_f32 v85, v201, 0x42440000, v75
	v_fmamk_f32 v74, v201, 0x41900000, v92
	v_fmamk_f32 v75, v201, 0x42480000, v76
	v_fmamk_f32 v76, v201, 0x41980000, v93
	v_fmamk_f32 v77, v201, 0x424c0000, v77
	v_fmamk_f32 v70, v201, 0x41c00000, v94
	v_fmamk_f32 v72, v201, 0x41c80000, v95
	v_fmamk_f32 v71, v201, 0x42600000, v78
	v_fmamk_f32 v73, v201, 0x42640000, v79
	v_fmamk_f32 v67, v201, 0x42680000, v80
	v_fmamk_f32 v69, v201, 0x426c0000, v81
	v_fmamk_f32 v66, v201, 0x41d00000, v96
	v_fmamk_f32 v68, v201, 0x41d80000, v97
	v_max3_f32 v78, v188, v234, v233
	v_max3_f32 v247, v82, v84, v83
	v_max3_f32 v78, v78, v235, v229
	v_max3_f32 v247, v247, v85, v74
	v_max3_f32 v78, v78, v230, v231
	v_max3_f32 v247, v247, v75, v76
	v_max3_f32 v78, v78, v232, v184
	v_max3_f32 v247, v247, v77, v70
	v_max3_f32 v78, v78, v227, v185
	v_max3_f32 v247, v247, v72, v71
	v_max3_f32 v78, v78, v228, v86
	v_max3_f32 v247, v247, v73, v67
	v_max3_f32 v78, v78, v88, v87
	v_max3_f32 v247, v247, v69, v66
	v_max_f32_e32 v78, v78, v89
	v_max_f32_e32 v247, v247, v68
	v_max_f32_e32 v78, v78, v247
	v_add_f32_e32 v78, v245, v78
	ds_bpermute_b32 v79, v1, v78
	s_waitcnt lgkmcnt(0)
	v_max_f32_e32 v79, v79, v79
	v_max_f32_e32 v78, v78, v79
	v_cmp_gt_f32_e32 vcc, v78, v226
	s_cbranch_vccz .LBB0_1400
	v_max_f32_e32 v78, v78, v78
	v_max_f32_e32 v79, v226, v226
	v_max_f32_e32 v79, v79, v78
	v_sub_f32_e32 v78, v226, v79
	v_exp_f32_e32 v78, v78
	v_mov_b32_e32 v226, v79
	v_mul_f32_e32 v224, v224, v78
	v_pk_mul_f32 v[64:65], v[64:65], v[78:79] op_sel_hi:[1,0]
	v_pk_mul_f32 v[62:63], v[62:63], v[78:79] op_sel_hi:[1,0]
	v_pk_mul_f32 v[60:61], v[60:61], v[78:79] op_sel_hi:[1,0]
	v_pk_mul_f32 v[58:59], v[58:59], v[78:79] op_sel_hi:[1,0]
	v_pk_mul_f32 v[56:57], v[56:57], v[78:79] op_sel_hi:[1,0]
	v_pk_mul_f32 v[54:55], v[54:55], v[78:79] op_sel_hi:[1,0]
	v_pk_mul_f32 v[52:53], v[52:53], v[78:79] op_sel_hi:[1,0]
	v_pk_mul_f32 v[50:51], v[50:51], v[78:79] op_sel_hi:[1,0]
	v_pk_mul_f32 v[48:49], v[48:49], v[78:79] op_sel_hi:[1,0]
	v_pk_mul_f32 v[46:47], v[46:47], v[78:79] op_sel_hi:[1,0]
	v_pk_mul_f32 v[44:45], v[44:45], v[78:79] op_sel_hi:[1,0]
	v_pk_mul_f32 v[42:43], v[42:43], v[78:79] op_sel_hi:[1,0]
	v_pk_mul_f32 v[40:41], v[40:41], v[78:79] op_sel_hi:[1,0]
	v_pk_mul_f32 v[38:39], v[38:39], v[78:79] op_sel_hi:[1,0]
	v_pk_mul_f32 v[36:37], v[36:37], v[78:79] op_sel_hi:[1,0]
	v_pk_mul_f32 v[34:35], v[34:35], v[78:79] op_sel_hi:[1,0]
	v_pk_mul_f32 v[32:33], v[32:33], v[78:79] op_sel_hi:[1,0]
	v_pk_mul_f32 v[30:31], v[30:31], v[78:79] op_sel_hi:[1,0]
	v_pk_mul_f32 v[28:29], v[28:29], v[78:79] op_sel_hi:[1,0]
	v_pk_mul_f32 v[26:27], v[26:27], v[78:79] op_sel_hi:[1,0]
	v_pk_mul_f32 v[24:25], v[24:25], v[78:79] op_sel_hi:[1,0]
	v_pk_mul_f32 v[22:23], v[22:23], v[78:79] op_sel_hi:[1,0]
	v_pk_mul_f32 v[20:21], v[20:21], v[78:79] op_sel_hi:[1,0]
	v_pk_mul_f32 v[18:19], v[18:19], v[78:79] op_sel_hi:[1,0]
	v_pk_mul_f32 v[16:17], v[16:17], v[78:79] op_sel_hi:[1,0]
	v_pk_mul_f32 v[14:15], v[14:15], v[78:79] op_sel_hi:[1,0]
	v_pk_mul_f32 v[12:13], v[12:13], v[78:79] op_sel_hi:[1,0]
	v_pk_mul_f32 v[10:11], v[10:11], v[78:79] op_sel_hi:[1,0]
	v_pk_mul_f32 v[8:9], v[8:9], v[78:79] op_sel_hi:[1,0]
	v_pk_mul_f32 v[6:7], v[6:7], v[78:79] op_sel_hi:[1,0]
	v_pk_mul_f32 v[4:5], v[4:5], v[78:79] op_sel_hi:[1,0]
	v_pk_mul_f32 v[2:3], v[2:3], v[78:79] op_sel_hi:[1,0]
.LBB0_1400:
	v_sub_f32_e32 v246, v226, v245
	v_sub_f32_e32 v78, v188, v246
	v_exp_f32_e32 v236, v78
	v_sub_f32_e32 v78, v233, v246
	v_exp_f32_e32 v237, v78
	v_sub_f32_e32 v78, v234, v246
	v_sub_f32_e32 v79, v235, v246
	v_exp_f32_e32 v78, v78
	v_exp_f32_e32 v188, v79
	v_add_f32_e32 v79, v236, v237
	v_sub_f32_e32 v86, v86, v246
	v_sub_f32_e32 v82, v82, v246
	v_pk_add_f32 v[80:81], v[78:79], v[188:189]
	v_sub_f32_e32 v79, v229, v246
	v_pk_add_f32 v[80:81], v[80:81], v[80:81] op_sel_hi:[0,1]
	v_sub_f32_e32 v80, v230, v246
	v_exp_f32_e32 v234, v80
	v_sub_f32_e32 v80, v231, v246
	v_exp_f32_e32 v79, v79
	v_exp_f32_e32 v90, v80
	v_sub_f32_e32 v80, v232, v246
	v_exp_f32_e32 v80, v80
	v_add_f32_e32 v91, v79, v234
	v_sub_f32_e32 v74, v74, v246
	v_sub_f32_e32 v70, v70, v246
	v_pk_add_f32 v[92:93], v[90:91], v[80:81]
	v_sub_f32_e32 v81, v184, v246
	v_pk_add_f32 v[92:93], v[92:93], v[92:93] op_sel_hi:[0,1]
	v_sub_f32_e32 v91, v185, v246
	v_sub_f32_e32 v92, v227, v246
	v_exp_f32_e32 v81, v81
	v_exp_f32_e32 v91, v91
	v_exp_f32_e32 v94, v92
	v_sub_f32_e32 v92, v228, v246
	v_exp_f32_e32 v92, v92
	v_add_f32_e32 v95, v81, v91
	v_sub_f32_e32 v66, v66, v246
	v_pk_add_f32 v[96:97], v[94:95], v[92:93]
	v_exp_f32_e32 v93, v86
	v_sub_f32_e32 v86, v87, v246
	v_pk_add_f32 v[96:97], v[96:97], v[96:97] op_sel_hi:[0,1]
	v_exp_f32_e32 v95, v86
	v_sub_f32_e32 v86, v88, v246
	v_sub_f32_e32 v87, v89, v246
	v_exp_f32_e32 v86, v86
	v_exp_f32_e32 v96, v87
	v_add_f32_e32 v87, v93, v95
	v_pk_add_f32 v[88:89], v[86:87], v[96:97]
	v_exp_f32_e32 v87, v82
	v_sub_f32_e32 v82, v83, v246
	v_pk_add_f32 v[88:89], v[88:89], v[88:89] op_sel_hi:[0,1]
	v_exp_f32_e32 v97, v82
	v_sub_f32_e32 v82, v84, v246
	v_sub_f32_e32 v83, v85, v246
	v_exp_f32_e32 v82, v82
	v_exp_f32_e32 v88, v83
	v_add_f32_e32 v83, v87, v97
	v_pk_add_f32 v[84:85], v[82:83], v[88:89]
	v_exp_f32_e32 v83, v74
	v_sub_f32_e32 v74, v75, v246
	v_exp_f32_e32 v89, v74
	v_sub_f32_e32 v74, v76, v246
	v_pk_add_f32 v[84:85], v[84:85], v[84:85] op_sel_hi:[0,1]
	v_exp_f32_e32 v76, v74
	v_sub_f32_e32 v74, v77, v246
	v_exp_f32_e32 v84, v74
	v_add_f32_e32 v77, v83, v89
	v_pk_add_f32 v[74:75], v[76:77], v[84:85]
	v_exp_f32_e32 v77, v70
	v_sub_f32_e32 v70, v71, v246
	v_exp_f32_e32 v85, v70
	v_sub_f32_e32 v70, v72, v246
	v_pk_add_f32 v[184:185], v[74:75], v[74:75] op_sel_hi:[0,1]
	v_exp_f32_e32 v228, v70
	v_sub_f32_e32 v70, v73, v246
	v_exp_f32_e32 v184, v70
	v_add_f32_e32 v229, v77, v85
	v_cvt_pk_bf16_f32 v72, v91, v92
	v_cvt_pk_bf16_f32 v73, v95, v96
	v_pk_add_f32 v[70:71], v[228:229], v[184:185]
	v_exp_f32_e32 v185, v66
	v_sub_f32_e32 v66, v67, v246
	v_exp_f32_e32 v227, v66
	v_sub_f32_e32 v66, v68, v246
	v_pk_add_f32 v[230:231], v[70:71], v[70:71] op_sel_hi:[0,1]
	v_exp_f32_e32 v232, v66
	v_sub_f32_e32 v66, v69, v246
	v_exp_f32_e32 v230, v66
	v_add_f32_e32 v233, v185, v227
	v_cvt_pk_bf16_f32 v68, v81, v94
	v_cvt_pk_bf16_f32 v69, v93, v86
	v_pk_add_f32 v[66:67], v[232:233], v[230:231]
	v_cvt_pk_bf16_f32 v70, v237, v188
	v_add_f32_e32 v66, v66, v67
	v_add_f32_e32 v224, v224, v66
	v_cvt_pk_bf16_f32 v66, v236, v78
	v_cvt_pk_bf16_f32 v67, v79, v90
	v_cvt_pk_bf16_f32 v71, v234, v80
	v_cvt_pk_bf16_f32 v74, v87, v82
	v_cvt_pk_bf16_f32 v75, v83, v76
	v_cvt_pk_bf16_f32 v76, v77, v228
	v_cvt_pk_bf16_f32 v77, v185, v232
	v_cvt_pk_bf16_f32 v78, v97, v88
	v_cvt_pk_bf16_f32 v79, v89, v84
	v_cvt_pk_bf16_f32 v80, v85, v184
	v_cvt_pk_bf16_f32 v81, v227, v230
	ds_read_b128 v[82:85], v221 offset:53312
	ds_read_b128 v[86:89], v221 offset:53344
	ds_read_b128 v[90:93], v221 offset:57920
	ds_read_b128 v[94:97], v221 offset:57952
	ds_read_b128 v[228:231], v221 offset:62528
	ds_read_b128 v[232:235], v221 offset:62560
	ds_read_b128 v[236:239], v225 offset:13888
	ds_read_b128 v[240:243], v225 offset:13920
	v_mfma_f32_32x32x16_bf16 v[50:65], v[166:169], v[66:69], v[50:65]
	v_mfma_f32_32x32x16_bf16 v[34:49], v[170:173], v[66:69], v[34:49]
	v_mfma_f32_32x32x16_bf16 v[18:33], v[174:177], v[66:69], v[18:33]
	v_mfma_f32_32x32x16_bf16 v[2:17], v[162:165], v[66:69], v[2:17]
	v_mfma_f32_32x32x16_bf16 v[50:65], v[150:153], v[74:77], v[50:65]
	v_mfma_f32_32x32x16_bf16 v[34:49], v[154:157], v[74:77], v[34:49]
	v_mfma_f32_32x32x16_bf16 v[18:33], v[158:161], v[74:77], v[18:33]
	v_mfma_f32_32x32x16_bf16 v[2:17], v[146:149], v[74:77], v[2:17]
	s_waitcnt lgkmcnt(7)
	v_mfma_f32_32x32x16_bf16 v[50:65], v[82:85], v[70:73], v[50:65]
	s_waitcnt lgkmcnt(5)
	v_mfma_f32_32x32x16_bf16 v[34:49], v[90:93], v[70:73], v[34:49]
	s_waitcnt lgkmcnt(3)
	v_mfma_f32_32x32x16_bf16 v[18:33], v[228:231], v[70:73], v[18:33]
	s_waitcnt lgkmcnt(1)
	v_mfma_f32_32x32x16_bf16 v[2:17], v[236:239], v[70:73], v[2:17]
	v_mfma_f32_32x32x16_bf16 v[50:65], v[86:89], v[78:81], v[50:65]
	v_mfma_f32_32x32x16_bf16 v[34:49], v[94:97], v[78:81], v[34:49]
	v_mfma_f32_32x32x16_bf16 v[18:33], v[232:235], v[78:81], v[18:33]
	s_waitcnt lgkmcnt(0)
	v_mfma_f32_32x32x16_bf16 v[2:17], v[240:243], v[78:81], v[2:17]
	s_cmp_ge_i32 s46, s26
	s_cbranch_scc1 .LBB0_1379

	.amdhsa_kernel _Z14fwd_megakernel6Params
		.amdhsa_group_segment_fixed_size 0
		.amdhsa_private_segment_fixed_size 0
		.amdhsa_kernarg_size 536
		.amdhsa_user_sgpr_count 2
		.amdhsa_user_sgpr_dispatch_ptr 0
		.amdhsa_user_sgpr_queue_ptr 0
		.amdhsa_user_sgpr_kernarg_segment_ptr 1
		.amdhsa_user_sgpr_dispatch_id 0
		.amdhsa_user_sgpr_kernarg_preload_length 0
		.amdhsa_user_sgpr_kernarg_preload_offset 0
		.amdhsa_user_sgpr_private_segment_size 0
		.amdhsa_uses_dynamic_stack 0
		.amdhsa_enable_private_segment 0
		.amdhsa_system_sgpr_workgroup_id_x 1
		.amdhsa_system_sgpr_workgroup_id_y 0
		.amdhsa_system_sgpr_workgroup_id_z 0
		.amdhsa_system_sgpr_workgroup_info 0
		.amdhsa_system_vgpr_workitem_id 0
		.amdhsa_next_free_vgpr 254
		.amdhsa_next_free_sgpr 98
		.amdhsa_accum_offset 256
		.amdhsa_reserve_vcc 1
		.amdhsa_float_round_mode_32 0
		.amdhsa_float_round_mode_16_64 0
		.amdhsa_float_denorm_mode_32 3
		.amdhsa_float_denorm_mode_16_64 3
		.amdhsa_dx10_clamp 1
		.amdhsa_ieee_mode 1
		.amdhsa_fp16_overflow 0
		.amdhsa_tg_split 0
		.amdhsa_exception_fp_ieee_invalid_op 0
		.amdhsa_exception_fp_denorm_src 0
		.amdhsa_exception_fp_ieee_div_zero 0
		.amdhsa_exception_fp_ieee_overflow 0
		.amdhsa_exception_fp_ieee_underflow 0
		.amdhsa_exception_fp_ieee_inexact 0
		.amdhsa_exception_int_div_zero 0
	.end_amdhsa_kernel

amdhsa.kernels:
  - .agpr_count:     0
    .args:
      - .offset:         0
        .size:           280
        .value_kind:     by_value
      - .offset:         280
        .size:           4
        .value_kind:     hidden_block_count_x
      - .offset:         284
        .size:           4
        .value_kind:     hidden_block_count_y
      - .offset:         288
        .size:           4
        .value_kind:     hidden_block_count_z
      - .offset:         292
        .size:           2
        .value_kind:     hidden_group_size_x
      - .offset:         294
        .size:           2
        .value_kind:     hidden_group_size_y
      - .offset:         296
        .size:           2
        .value_kind:     hidden_group_size_z
      - .offset:         298
        .size:           2
        .value_kind:     hidden_remainder_x
      - .offset:         300
        .size:           2
        .value_kind:     hidden_remainder_y
      - .offset:         302
        .size:           2
        .value_kind:     hidden_remainder_z
      - .offset:         320
        .size:           8
        .value_kind:     hidden_global_offset_x
      - .offset:         328
        .size:           8
        .value_kind:     hidden_global_offset_y
      - .offset:         336
        .size:           8
        .value_kind:     hidden_global_offset_z
      - .offset:         344
        .size:           2
        .value_kind:     hidden_grid_dims
      - .offset:         400
        .size:           4
        .value_kind:     hidden_dynamic_lds_size
    .group_segment_fixed_size: 0
    .kernarg_segment_align: 8
    .kernarg_segment_size: 536
    .language:       OpenCL C
    .language_version:
      - 2
      - 0
    .max_flat_workgroup_size: 512
    .name:           _Z14fwd_megakernel6Params
    .private_segment_fixed_size: 0
    .sgpr_count:     104
    .sgpr_spill_count: 56
    .symbol:         _Z14fwd_megakernel6Params.kd
    .uniform_work_group_size: 1
    .uses_dynamic_stack: false
    .vgpr_count:     254
    .vgpr_spill_count: 0
    .wavefront_size: 64
